# v12 + 2048 layer-1 fp8 conversion items moved from branch tail (6->5 rounds) to in-proj idle workgroups
# speedup vs baseline: 1.0002x; 1.0002x over previous
.LBB0_80:
	v_readlane_b32 s22, v248, 1
	v_readlane_b32 s23, v248, 2
	s_add_u32 s0, s22, 0x72d00000
	s_addc_u32 s1, s23, 0
	v_writelane_b32 v249, s0, 4
	v_readlane_b32 s24, v248, 7
	v_readlane_b32 s48, v248, 26
	v_writelane_b32 v249, s1, 5
	s_ashr_i32 s0, s24, 31
	v_readlane_b32 s50, v248, 28
	v_writelane_b32 v249, s0, 6
	v_readlane_b32 s51, v248, 29
	s_add_u32 s0, s50, 0x2000
	s_addc_u32 s1, s51, 0
	v_writelane_b32 v249, s0, 7
	s_cmpk_lg_i32 s24, 0x100
	v_readlane_b32 s13, v248, 43
	v_writelane_b32 v249, s1, 8
	s_cselect_b64 s[0:1], -1, 0
	v_writelane_b32 v249, s0, 9
	s_cmpk_lt_i32 s13, 0x1400
	v_readlane_b32 s21, v248, 0
	v_writelane_b32 v249, s1, 10
	s_cselect_b64 s[0:1], -1, 0
	v_writelane_b32 v249, s0, 11
	v_readlane_b32 s49, v248, 27
	v_mov_b32_e32 v34, 0
	v_writelane_b32 v249, s1, 12
	s_add_i32 s0, s13, 0x3c80
	s_add_u32 s9, s22, 0x24500000
	s_addc_u32 s12, s23, 0
	s_add_u32 s5, s22, 0x1e500000
	v_writelane_b32 v249, s0, 13
	s_addc_u32 s11, s23, 0
	s_add_i32 s0, s21, 0xffffff97
	s_cmpk_lt_u32 s0, 0x67
	s_cselect_b64 s[0:1], -1, 0
	v_writelane_b32 v249, s0, 14
	v_mov_b32_e32 v219, 1
	v_mov_b32_e32 v222, 0x358637bd
	v_writelane_b32 v249, s1, 15
	s_add_i32 s0, s13, 0xfffffcb8
	s_cmpk_lt_i32 s0, 0x1400
	s_cselect_b64 s[0:1], -1, 0
	v_writelane_b32 v249, s0, 16
	v_mov_b32_e32 v223, 0x260
	v_mov_b32_e32 v224, 0x3ecc95a3
	v_writelane_b32 v249, s1, 17
	s_add_i32 s0, s13, 0x3938
	v_writelane_b32 v249, s0, 18
	s_add_u32 s0, s22, 0x4200
	s_addc_u32 s1, s23, 0
	v_writelane_b32 v249, s0, 19
	v_mov_b32_e32 v225, 0x3e2aaaab
	v_mov_b64_e32 v[164:165], 0x969
	v_writelane_b32 v249, s1, 20
	s_add_u32 s0, s22, 0x4400
	s_addc_u32 s1, s23, 0
	v_writelane_b32 v249, s0, 21
	v_mov_b64_e32 v[166:167], 0x968
	v_mov_b32_e32 v226, 0x41b17218
	v_writelane_b32 v249, s1, 22
	s_add_u32 s0, s22, 0x4500
	s_addc_u32 s1, s23, 0
	v_writelane_b32 v249, s0, 23
	v_mov_b64_e32 v[168:169], 0x630
	v_mov_b64_e32 v[170:171], 0x62f
	v_writelane_b32 v249, s1, 24
	s_add_u32 s0, s22, 0x4600
	s_addc_u32 s1, s23, 0
	v_writelane_b32 v249, s0, 25
	v_mov_b32_e32 v227, 0x1e040
	v_mov_b32_e32 v228, 2
	v_writelane_b32 v249, s1, 26
	s_add_u32 s0, s22, 0x4700
	s_addc_u32 s1, s23, 0
	v_writelane_b32 v249, s0, 27
	v_mov_b32_e32 v230, 0x3000
	v_mov_b32_e32 v231, 0x7f800000
	v_writelane_b32 v249, s1, 28
	s_add_u32 s0, s22, 0x4800
	s_addc_u32 s1, s23, 0
	v_writelane_b32 v249, s0, 29
	v_readlane_b32 s52, v248, 30
	v_readlane_b32 s53, v248, 31
	v_writelane_b32 v249, s1, 30
	s_add_u32 s0, s22, 0x4900
	s_addc_u32 s1, s23, 0
	v_writelane_b32 v249, s0, 31
	v_readlane_b32 s54, v248, 32
	v_readlane_b32 s55, v248, 33
	v_writelane_b32 v249, s1, 32
	s_add_u32 s0, s22, 0x4a00
	s_addc_u32 s1, s23, 0
	v_writelane_b32 v249, s0, 33
	v_readlane_b32 s56, v248, 34
	v_readlane_b32 s57, v248, 35
	v_writelane_b32 v249, s1, 34
	s_add_u32 s0, s22, 0x4b00
	s_addc_u32 s1, s23, 0
	v_writelane_b32 v249, s0, 35
	v_readlane_b32 s58, v248, 36
	v_readlane_b32 s59, v248, 37
	v_writelane_b32 v249, s1, 36
	s_add_u32 s0, s22, 0x4c00
	s_addc_u32 s1, s23, 0
	v_writelane_b32 v249, s0, 37
	v_readlane_b32 s60, v248, 38
	v_readlane_b32 s61, v248, 39
	v_writelane_b32 v249, s1, 38
	s_add_u32 s0, s22, 0x4d00
	s_addc_u32 s1, s23, 0
	v_writelane_b32 v249, s0, 39
	v_readlane_b32 s62, v248, 40
	v_readlane_b32 s63, v248, 41
	v_writelane_b32 v249, s1, 40
	s_add_u32 s0, s22, 0x4e00
	s_addc_u32 s1, s23, 0
	v_writelane_b32 v249, s0, 41
	s_nop 1
	v_writelane_b32 v249, s1, 42
	s_add_u32 s0, s22, 0x4f00
	s_addc_u32 s1, s23, 0
	v_writelane_b32 v249, s0, 43
	s_nop 1
	v_writelane_b32 v249, s1, 44
	s_add_u32 s0, s22, 0x5000
	s_addc_u32 s1, s23, 0
	v_writelane_b32 v249, s0, 45
	s_nop 1
	v_writelane_b32 v249, s1, 46
	s_add_u32 s0, s22, 0x5100
	s_addc_u32 s1, s23, 0
	v_writelane_b32 v249, s0, 47
	s_nop 1
	v_writelane_b32 v249, s1, 48
	s_add_u32 s0, s22, 0x5200
	s_addc_u32 s1, s23, 0
	v_writelane_b32 v249, s0, 49
	s_nop 1
	v_writelane_b32 v249, s1, 50
	s_add_u32 s0, s22, 0x5300
	s_addc_u32 s1, s23, 0
	v_writelane_b32 v249, s0, 51
	s_cmp_eq_u32 s46, 15
	s_nop 0
	v_writelane_b32 v249, s1, 52
	s_cselect_b64 s[0:1], -1, 0
	v_writelane_b32 v249, s0, 53
	s_cmp_eq_u32 s46, 14
	s_nop 0
	v_writelane_b32 v249, s1, 54
	s_cselect_b64 s[0:1], -1, 0
	v_writelane_b32 v249, s0, 55
	s_cmp_eq_u32 s46, 13
	s_nop 0
	v_writelane_b32 v249, s1, 56
	s_cselect_b64 s[0:1], -1, 0
	v_writelane_b32 v249, s0, 57
	s_cmp_eq_u32 s46, 12
	s_nop 0
	v_writelane_b32 v249, s1, 58
	s_cselect_b64 s[0:1], -1, 0
	v_writelane_b32 v249, s0, 59
	s_cmp_eq_u32 s46, 11
	s_nop 0
	v_writelane_b32 v249, s1, 60
	s_cselect_b64 s[0:1], -1, 0
	v_writelane_b32 v249, s0, 61
	s_cmp_eq_u32 s46, 10
	s_nop 0
	v_writelane_b32 v249, s1, 62
	s_cselect_b64 s[0:1], -1, 0
	v_writelane_b32 v249, s0, 63
	s_cmp_eq_u32 s46, 9
	s_nop 0
	v_writelane_b32 v250, s1, 0
	s_cselect_b64 s[0:1], -1, 0
	v_writelane_b32 v250, s0, 1
	s_cmp_eq_u32 s46, 8
	s_nop 0
	v_writelane_b32 v250, s1, 2
	s_cselect_b64 s[0:1], -1, 0
	v_writelane_b32 v250, s0, 3
	s_cmp_eq_u32 s46, 7
	s_nop 0
	v_writelane_b32 v250, s1, 4
	s_cselect_b64 s[0:1], -1, 0
	v_writelane_b32 v250, s0, 5
	s_cmp_eq_u32 s46, 6
	s_nop 0
	v_writelane_b32 v250, s1, 6
	s_cselect_b64 s[0:1], -1, 0
	v_writelane_b32 v250, s0, 7
	s_cmp_eq_u32 s46, 5
	s_nop 0
	v_writelane_b32 v250, s1, 8
	s_cselect_b64 s[0:1], -1, 0
	v_writelane_b32 v250, s0, 9
	s_cmp_eq_u32 s46, 4
	s_nop 0
	v_writelane_b32 v250, s1, 10
	s_cselect_b64 s[0:1], -1, 0
	v_writelane_b32 v250, s0, 11
	s_cmp_eq_u32 s46, 3
	s_nop 0
	v_writelane_b32 v250, s1, 12
	s_cselect_b64 s[0:1], -1, 0
	v_writelane_b32 v250, s0, 13
	s_cmp_eq_u32 s46, 2
	s_nop 0
	v_writelane_b32 v250, s1, 14
	s_cselect_b64 s[0:1], -1, 0
	v_writelane_b32 v250, s0, 15
	s_cmp_eq_u32 s46, 1
	s_nop 0
	v_writelane_b32 v250, s1, 16
	s_cselect_b64 s[0:1], -1, 0
	v_writelane_b32 v250, s0, 17
	s_cmp_eq_u32 s46, 0
	s_nop 0
	v_writelane_b32 v250, s1, 18
	s_cselect_b64 s[0:1], -1, 0
	v_writelane_b32 v250, s0, 19
	s_nop 1
	v_writelane_b32 v250, s1, 20
	s_lshl_b32 s0, s46, 8
	s_add_u32 s0, s2, s0
	s_addc_u32 s1, s3, 0
	s_add_u32 s2, s0, 0x1400
	s_addc_u32 s3, s1, 0
	v_writelane_b32 v250, s2, 21
	s_add_u32 s0, s0, 0x2400
	s_addc_u32 s1, s1, 0
	v_writelane_b32 v250, s3, 22
	v_writelane_b32 v250, s0, 23
	s_nop 1
	v_writelane_b32 v250, s1, 24
	s_add_u32 s0, s22, 0x7400
	s_addc_u32 s1, s23, 0
	v_writelane_b32 v250, s0, 25
	s_nop 1
	v_writelane_b32 v250, s1, 26
	s_add_u32 s0, s22, 0x7500
	s_addc_u32 s1, s23, 0
	v_writelane_b32 v250, s0, 27
	s_cmpk_lt_i32 s21, 0x220
	s_nop 0
	v_writelane_b32 v250, s1, 28
	s_cselect_b64 s[0:1], -1, 0
	v_writelane_b32 v250, s0, 29
	s_ashr_i32 s14, s21, 31
	s_add_i32 s8, s21, 0xffffff40
	v_writelane_b32 v250, s1, 30
	s_lshr_b32 s0, s14, 26
	s_add_i32 s0, s21, s0
	s_ashr_i32 s7, s0, 6
	s_add_i32 s0, s24, 0xffffff40
	v_writelane_b32 v250, s0, 31
	s_sub_i32 s0, s21, 64
	s_cmpk_lt_i32 s21, 0x80
	s_cselect_b32 s25, s21, s0
	s_cmpk_lt_i32 s25, 0x220
	v_writelane_b32 v250, s0, 32
	s_cselect_b64 s[0:1], -1, 0
	v_writelane_b32 v250, s0, 33
	s_nop 1
	v_writelane_b32 v250, s1, 34
	s_add_u32 s0, s22, 0x12000
	v_writelane_b32 v250, s0, 35
	s_addc_u32 s0, s23, 0
	v_writelane_b32 v250, s0, 36
	s_add_i32 s0, s21, 0xffffff80
	v_writelane_b32 v250, s0, 37
	s_add_i32 s0, s21, 1
	v_writelane_b32 v250, s0, 38
	s_sub_i32 s0, s21, 63
	v_writelane_b32 v250, s0, 39
	s_add_i32 s0, s21, 0xffffff81
	s_cmpk_gt_i32 s21, 0xbf
	v_writelane_b32 v250, s0, 40
	s_cselect_b64 s[0:1], -1, 0
	s_cmpk_eq_i32 s24, 0x100
	s_cselect_b64 s[26:27], -1, 0
	s_and_b64 s[2:3], s[26:27], exec
	s_movk_i32 s2, 0x200
	s_cselect_b32 s6, s2, 0x210
	s_movk_i32 s2, 0x2000
	s_cselect_b32 s2, s2, 0x2100
	v_writelane_b32 v250, s2, 41
	s_cselect_b32 s19, 32, 33
	s_cselect_b32 s10, 0xc80, 0
	s_and_b64 s[0:1], s[0:1], s[26:27]
	v_writelane_b32 v250, s0, 42
	s_nop 1
	v_writelane_b32 v250, s1, 43
	s_add_u32 s0, s22, 0x10000
	v_writelane_b32 v250, s0, 44
	s_addc_u32 s0, s23, 0
	v_writelane_b32 v250, s0, 45
	s_lshl_b32 s0, s8, 3
	s_add_i32 s15, s33, s0
	s_cmpk_lt_i32 s21, 0xf0
	s_mul_hi_i32 s0, s8, 0x55555556
	s_cselect_b64 s[2:3], -1, 0
	s_lshr_b32 s1, s0, 31
	s_add_i32 s1, s0, s1
	s_mul_i32 s0, s1, -3
	v_writelane_b32 v250, s2, 46
	s_add_i32 s0, s0, s8
	s_mul_i32 s4, s1, 0x300000
	v_writelane_b32 v250, s3, 47
	s_lshl_b32 s2, s0, 11
	s_ashr_i32 s3, s2, 31
	s_lshl_b64 s[28:29], s[2:3], 1
	s_add_u32 s2, s5, s28
	v_writelane_b32 v250, s5, 48
	s_addc_u32 s3, s11, s29
	v_writelane_b32 v250, s11, 49
	s_add_u32 s2, s2, s4
	s_mul_hi_i32 s5, s1, 0x300000
	v_writelane_b32 v250, s2, 50
	s_addc_u32 s2, s3, s5
	v_writelane_b32 v250, s2, 51
	s_lshl_b32 s1, s1, 8
	v_writelane_b32 v250, s1, 52
	s_ashr_i32 s1, s0, 31
	s_lshl_b64 s[2:3], s[0:1], 12
	v_writelane_b32 v250, s2, 53
	s_lshl_b64 s[0:1], s[0:1], 22
	s_ashr_i32 s8, s8, 2
	v_writelane_b32 v250, s3, 54
	v_writelane_b32 v250, s0, 55
	s_nop 1
	v_writelane_b32 v250, s1, 56
	s_and_b32 s0, s21, 3
	s_lshl_b32 s2, s0, 10
	s_lshl_b32 s30, s0, 11
	v_writelane_b32 v250, s9, 57
	s_add_u32 s11, s9, s30
	v_writelane_b32 v250, s12, 58
	s_addc_u32 s12, s12, 0
	s_ashr_i32 s9, s8, 31
	s_lshl_b32 s3, s0, 20
	s_lshl_b64 s[0:1], s[8:9], 21
	s_add_u32 s9, s11, s0
	v_writelane_b32 v250, s9, 59
	s_addc_u32 s9, s12, s1
	v_writelane_b32 v250, s9, 60
	s_lshl_b32 s8, s8, 8
	v_writelane_b32 v250, s8, 61
	s_cmpk_lt_i32 s15, 0xc80
	v_writelane_b32 v250, s15, 62
	s_cselect_b64 s[8:9], -1, 0
	v_writelane_b32 v250, s8, 63
	s_nop 1
	v_writelane_b32 v251, s9, 0
	s_add_u32 s8, s48, 0x1e040000
	s_addc_u32 s9, s49, 0
	v_writelane_b32 v251, s8, 1
	v_readlane_b32 s36, v248, 10
	v_readlane_b32 s50, v248, 24
	v_writelane_b32 v251, s9, 2
	s_add_u32 s8, s22, 0xf300000
	s_addc_u32 s9, s23, 0
	s_lshl_b32 s34, s19, 4
	v_writelane_b32 v251, s8, 3
	s_cmp_lt_i32 s21, s34
	v_readlane_b32 s51, v248, 25
	v_writelane_b32 v251, s9, 4
	s_cselect_b64 s[8:9], -1, 0
	v_writelane_b32 v251, s8, 5
	s_add_i32 s16, s24, s6
	s_add_i32 s20, s19, -8
	v_writelane_b32 v251, s9, 6
	s_lshr_b32 s8, s14, 29
	s_add_i32 s8, s21, s8
	v_writelane_b32 v251, s14, 7
	s_ashr_i32 s14, s8, 3
	s_and_b32 s8, s8, -8
	s_sub_i32 s15, s21, s8
	s_add_i32 s17, s16, -1
	s_add_i32 s8, s13, s10
	s_cmpk_lt_i32 s8, 0x3480
	v_writelane_b32 v251, s8, 8
	s_cselect_b64 s[8:9], -1, 0
	v_writelane_b32 v251, s8, 9
	v_readlane_b32 s48, v248, 22
	v_readlane_b32 s49, v248, 23
	v_writelane_b32 v251, s9, 10
	s_add_u32 s8, s22, 0x85300000
	s_addc_u32 s9, s23, 0
	s_lshl_b32 s31, s19, 1
	v_writelane_b32 v251, s8, 11
	s_add_i32 s18, s10, s33
	s_or_b32 s33, s31, 1
	v_writelane_b32 v251, s9, 12
	s_add_u32 s8, s22, 0x76d00000
	v_writelane_b32 v251, s8, 13
	s_addc_u32 s8, s23, 0
	v_writelane_b32 v251, s8, 14
	s_add_u32 s8, s50, 0x4000
	s_addc_u32 s9, s51, 0
	v_writelane_b32 v251, s8, 15
	v_mov_b32_e32 v1, s15
	v_alignbit_b32 v1, s19, v1, 31
	v_writelane_b32 v251, s9, 16
	s_add_u32 s8, s48, 0x4000
	s_addc_u32 s9, s49, 0
	v_writelane_b32 v251, s8, 17
	v_readlane_b32 s37, v248, 11
	v_readlane_b32 s38, v248, 12
	v_writelane_b32 v251, s9, 18
	v_readlane_b32 s8, v248, 3
	v_readlane_b32 s9, v248, 4
	s_mov_b64 s[12:13], s[8:9]
	s_cmp_gt_i32 s12, 7
	v_readlane_b32 s10, v248, 5
	v_readlane_b32 s11, v248, 6
	s_cselect_b64 s[8:9], -1, 0
	s_cmp_lt_i32 s13, 9
	s_cselect_b64 s[10:11], -1, 0
	s_cmpk_lt_i32 s21, 0xc0
	s_cselect_b32 s7, s7, -1
	s_cmpk_gt_i32 s24, 0xc0
	s_cselect_b32 s7, s7, -2
	s_cmp_lg_u32 s7, 2
	s_cselect_b64 s[12:13], -1, 0
	v_writelane_b32 v251, s26, 19
	s_and_b64 s[12:13], s[26:27], s[12:13]
	s_cmp_lg_u32 s7, 1
	v_writelane_b32 v251, s27, 20
	v_writelane_b32 v251, s12, 21
	v_readlane_b32 s39, v248, 13
	v_readlane_b32 s40, v248, 14
	v_writelane_b32 v251, s13, 22
	v_writelane_b32 v251, s7, 23
	v_readfirstlane_b32 s7, v1
	v_writelane_b32 v251, s19, 24
	s_mul_i32 s7, s7, s15
	s_cselect_b64 s[12:13], -1, 0
	v_writelane_b32 v251, s12, 25
	s_add_i32 s7, s7, s14
	v_readlane_b32 s41, v248, 15
	v_writelane_b32 v251, s13, 26
	s_ashr_i32 s12, s7, 31
	s_lshr_b32 s12, s12, 25
	s_add_i32 s12, s7, s12
	s_ashr_i32 s12, s12, 7
	s_lshl_b32 s13, s12, 7
	s_sub_i32 s7, s7, s13
	s_lshl_b32 s12, s12, 3
	s_cmp_gt_i32 s12, s20
	s_cselect_b32 s13, 1, 8
	s_cmp_lt_i32 s15, 0
	s_cselect_b32 s19, s33, s31
	s_mul_i32 s15, s19, s15
	s_add_i32 s14, s15, s14
	v_cvt_f32_ubyte0_e32 v1, s13
	s_ashr_i32 s15, s14, 31
	v_rcp_iflag_f32_e32 v1, v1
	s_lshr_b32 s15, s15, 25
	s_add_i32 s15, s14, s15
	s_ashr_i32 s15, s15, 7
	s_lshl_b32 s19, s15, 7
	v_mul_f32_e32 v1, 0x4f7ffffe, v1
	v_writelane_b32 v251, s31, 27
	s_sub_i32 s14, s14, s19
	s_lshl_b32 s15, s15, 3
	v_cvt_u32_f32_e32 v1, v1
	v_writelane_b32 v251, s33, 28
	s_cmp_gt_i32 s15, s20
	v_writelane_b32 v251, s20, 29
	s_cselect_b32 s19, 1, 8
	s_or_b64 s[8:9], s[8:9], s[10:11]
	v_writelane_b32 v251, s8, 30
	s_mov_b32 s33, 0xbcf5c28f
	v_readlane_b32 s42, v248, 16
	v_writelane_b32 v251, s9, 31
	s_sub_i32 s8, 0, s13
	v_readfirstlane_b32 s9, v1
	s_mul_i32 s8, s8, s9
	s_mul_hi_u32 s8, s9, s8
	s_add_i32 s9, s9, s8
	s_abs_i32 s8, s7
	s_mul_hi_u32 s9, s8, s9
	s_mul_i32 s10, s9, s13
	s_sub_i32 s8, s8, s10
	s_ashr_i32 s10, s7, 31
	s_add_i32 s11, s9, 1
	s_sub_i32 s20, s8, s13
	s_cmp_ge_u32 s8, s13
	s_cselect_b32 s9, s11, s9
	s_cselect_b32 s8, s20, s8
	s_add_i32 s11, s9, 1
	s_cmp_ge_u32 s8, s13
	s_cselect_b32 s8, s11, s9
	s_xor_b32 s8, s8, s10
	s_sub_i32 s8, s8, s10
	v_writelane_b32 v251, s8, 32
	s_mul_i32 s8, s8, s13
	s_sub_i32 s7, s7, s8
	s_add_i32 s7, s12, s7
	v_writelane_b32 v251, s7, 33
	s_abs_i32 s7, s24
	v_cvt_f32_u32_e32 v1, s7
	s_sub_i32 s8, 0, s7
	v_readlane_b32 s43, v248, 17
	v_readlane_b32 s44, v248, 18
	v_rcp_iflag_f32_e32 v1, v1
	v_readlane_b32 s45, v248, 19
	v_readlane_b32 s46, v248, 20
	v_readlane_b32 s47, v248, 21
	v_mul_f32_e32 v1, 0x4f7ffffe, v1
	v_cvt_u32_f32_e32 v1, v1
	s_nop 0
	v_readfirstlane_b32 s9, v1
	s_mul_i32 s8, s8, s9
	s_mul_hi_u32 s8, s9, s8
	s_add_i32 s9, s9, s8
	s_sub_i32 s8, 1, s16
	s_max_i32 s8, s17, s8
	s_mul_hi_u32 s9, s8, s9
	s_mul_i32 s10, s9, s7
	s_sub_i32 s8, s8, s10
	s_xor_b32 s10, s17, s24
	s_ashr_i32 s10, s10, 31
	s_add_i32 s11, s9, 1
	s_sub_i32 s12, s8, s7
	s_cmp_ge_u32 s8, s7
	s_cselect_b32 s9, s11, s9
	s_cselect_b32 s8, s12, s8
	s_add_i32 s11, s9, 1
	s_cmp_ge_u32 s8, s7
	s_cselect_b32 s7, s11, s9
	s_xor_b32 s7, s7, s10
	s_not_b32 s8, s10
	s_add_i32 s7, s8, s7
	s_mul_i32 s7, s7, s24
	s_sub_i32 s6, s6, s7
	s_sub_i32 s7, s24, s6
	v_cvt_f32_ubyte0_e32 v1, s19
	s_cmp_lt_i32 s7, 1
	v_rcp_iflag_f32_e32 v1, v1
	s_cselect_b64 s[8:9], -1, 0
	v_writelane_b32 v251, s8, 34
	s_cmp_ge_i32 s21, s6
	v_mul_f32_e32 v1, 0x4f7ffffe, v1
	v_writelane_b32 v251, s9, 35
	s_cselect_b64 s[8:9], -1, 0
	s_sub_i32 s6, s21, s6
	v_writelane_b32 v251, s8, 36
	s_lshl_b32 s6, s6, 3
	s_add_i32 s6, s18, s6
	v_writelane_b32 v251, s9, 37
	s_lshl_b32 s7, s7, 3
	v_cvt_u32_f32_e32 v1, v1
	v_writelane_b32 v251, s7, 38
	s_cmpk_lt_i32 s6, 0x3c80
	v_writelane_b32 v251, s6, 39
	s_cselect_b64 s[6:7], -1, 0
	v_writelane_b32 v251, s6, 40
	s_nop 1
	v_writelane_b32 v251, s7, 41
	s_sub_i32 s6, 0, s19
	v_readfirstlane_b32 s7, v1
	s_mul_i32 s6, s6, s7
	s_mul_hi_u32 s6, s7, s6
	s_add_i32 s7, s7, s6
	s_abs_i32 s6, s14
	s_mul_hi_u32 s7, s6, s7
	s_mul_i32 s8, s7, s19
	s_sub_i32 s6, s6, s8
	s_ashr_i32 s8, s14, 31
	s_add_i32 s9, s7, 1
	s_sub_i32 s10, s6, s19
	s_cmp_ge_u32 s6, s19
	s_cselect_b32 s7, s9, s7
	s_cselect_b32 s6, s10, s6
	s_add_i32 s9, s7, 1
	s_cmp_ge_u32 s6, s19
	s_cselect_b32 s6, s9, s7
	s_xor_b32 s6, s6, s8
	s_sub_i32 s8, s6, s8
	s_mul_i32 s6, s8, s19
	s_sub_i32 s6, s14, s6
	s_add_i32 s10, s15, s6
	s_lshl_b32 s6, s21, 8
	v_writelane_b32 v251, s6, 42
	s_lshl_b32 s6, s24, 8
	v_writelane_b32 v251, s6, 43
	v_writelane_b32 v251, s25, 44
	s_lshl_b32 s6, s25, 8
	v_writelane_b32 v251, s6, 45
	s_mov_b32 s6, s10
	s_ashr_i32 s11, s10, 31
	v_writelane_b32 v251, s6, 46
	s_ashr_i32 s9, s8, 31
	v_mbcnt_lo_u32_b32 v1, -1, 0
	v_writelane_b32 v251, s7, 47
	s_lshl_b64 s[6:7], s[10:11], 21
	v_writelane_b32 v251, s6, 48
	v_mbcnt_hi_u32_b32 v229, -1, v1
	s_nop 0
	v_writelane_b32 v251, s7, 49
	s_mov_b32 s6, s8
	v_writelane_b32 v251, s6, 50
	s_nop 1
	v_writelane_b32 v251, s7, 51
	s_lshl_b64 s[6:7], s[8:9], 21
	s_add_u32 s4, s4, s28
	s_addc_u32 s5, s5, s29
	s_add_u32 s4, s22, s4
	v_writelane_b32 v251, s6, 52
	s_addc_u32 s5, s23, s5
	s_add_u32 s4, s4, 0x1e500100
	v_writelane_b32 v251, s7, 53
	v_writelane_b32 v251, s4, 54
	s_addc_u32 s4, s5, 0
	v_writelane_b32 v251, s4, 55
	s_add_u32 s4, s28, 0x55b80080
	v_writelane_b32 v251, s4, 56
	v_writelane_b32 v251, s28, 57
	s_addc_u32 s4, s29, 0
	s_or_b32 s0, s0, s30
	v_writelane_b32 v251, s29, 58
	s_mov_b32 s5, 0
	v_writelane_b32 v251, s4, 59
	s_add_u32 s0, s22, s0
	s_mov_b32 s35, s5
	s_addc_u32 s1, s23, s1
	v_writelane_b32 v251, s34, 60
	s_add_u32 s0, s0, 0x24500100
	s_mov_b64 s[6:7], -1
	v_writelane_b32 v251, s35, 61
	v_writelane_b32 v251, s0, 62
	s_addc_u32 s0, s1, 0
	v_writelane_b32 v251, s0, 63
	s_mul_hi_i32 s1, s66, 0x3000
	s_mul_i32 s0, s66, 0x3000
	v_writelane_b32 v252, s0, 0
	s_ashr_i32 s67, s66, 31
	s_mov_b32 s12, s5
	v_writelane_b32 v252, s1, 1
	s_lshl_b32 s0, s2, 1
	v_writelane_b32 v252, s0, 2
	s_lshl_b32 s0, s3, 2
	v_writelane_b32 v252, s0, 3
	v_writelane_b32 v252, s30, 4
	s_or_b32 s0, s30, 0x6a800080
	v_writelane_b32 v252, s0, 5
	s_add_i32 s0, 0, 0x19800
	v_writelane_b32 v252, s0, 6
	v_cmp_eq_u32_e64 s[0:1], 0, v0
	s_mov_b64 s[2:3], 0x80
	s_nop 0
	v_writelane_b32 v252, s0, 7
	s_nop 1
	v_writelane_b32 v252, s1, 8
	s_lshl_b64 s[0:1], s[66:67], 12
	v_writelane_b32 v252, s0, 9
	s_nop 1
	v_writelane_b32 v252, s1, 10
	s_lshl_b64 s[0:1], s[66:67], 7
	v_writelane_b32 v252, s0, 11
	s_nop 1
	v_writelane_b32 v252, s1, 12
	s_lshl_b64 s[0:1], s[66:67], 13
	v_writelane_b32 v252, s0, 13
	s_nop 1
	v_writelane_b32 v252, s1, 14
	s_mov_b32 s1, 0
	v_writelane_b32 v252, s0, 15
	s_nop 1
	v_writelane_b32 v252, s1, 16
	v_writelane_b32 v252, s66, 17
	s_nop 1
	v_writelane_b32 v252, s67, 18
	s_branch .LBB0_84

.LBB0_314:
	s_andn2_b64 vcc, exec, s[6:7]
	s_cbranch_vccnz .LBB0_343
	v_readlane_b32 s6, v249, 14
	v_readlane_b32 s7, v249, 15
	s_andn2_b64 vcc, exec, s[6:7]
	s_cbranch_vccnz .LBB0_343
	v_readlane_b32 s6, v249, 16
	v_readlane_b32 s7, v249, 17
	v_and_b32_e32 v2, 63, v0
	s_andn2_b64 vcc, exec, s[6:7]
	s_cbranch_vccnz .LBB0_343
	v_lshlrev_b32_e32 v1, 3, v2
	s_waitcnt vmcnt(0) lgkmcnt(0)
	v_lshlrev_b32_e32 v137, 4, v2
	v_readlane_b32 s13, v249, 18
	v_lshlrev_b32_e32 v7, 1, v2
	v_lshlrev_b32_e32 v35, 8, v2
	v_ashrrev_i32_e32 v136, 3, v2
	v_and_b32_e32 v6, 56, v1
	v_add_u32_e32 v138, 0x4810, v2
	v_lshlrev_b32_e32 v139, 7, v2
	v_and_b32_e32 v8, 0x70, v137
	v_mov_b32_e32 v9, v34
	s_lshl_b32 s11, s13, 7
	s_lshl_b32 s12, s13, 1
	v_readlane_b32 s98, v252, 27
	s_movk_i32 s99, 0x4d47
	s_nop 1
	s_cmp_eq_u32 s98, 0
	s_cselect_b32 s98, 0x800, 0
	s_add_i32 s99, s99, s98
	s_mov_b32 s98, 0
	s_branch .LBB0_320

.LBB0_320:
	s_cmpk_lt_i32 s13, 0x5080
	s_cbranch_scc1 .Lcv_norm
	s_mov_b32 s98, s13
	s_sub_i32 s13, s13, 0x1c00
	v_readlane_b32 s6, v252, 15
	v_readlane_b32 s7, v252, 16
	s_nop 1
	v_writelane_b32 v253, s6, 47
	v_writelane_b32 v253, s7, 48
	s_add_u32 s36, s36, 0x1e040000
	s_addc_u32 s37, s37, 0
	s_add_u32 s38, s38, 0x3000000
	s_addc_u32 s39, s39, 0

.LBB0_1642:
	s_add_i32 s10, s10, s66
	s_add_i32 s8, s8, s9
	s_cmpk_lt_i32 s10, 0x3480
	s_cbranch_scc0 .LBB0_1654
